# foxc prefix items are now handled only by the waves that do not run the gla/lru chunk scans (scan waves start their scan immediately)
# speedup vs baseline: 1.0034x; 1.0034x over previous
.LBB0_208:
	s_or_b64 exec, exec, s[0:1]
	s_barrier
	s_mov_b64 s[0:1], exec
	v_readlane_b32 s2, v245, 45
	v_readlane_b32 s3, v245, 46
	s_and_b64 s[2:3], s[0:1], s[2:3]
	s_mov_b64 exec, s[2:3]
	s_cbranch_execz .LBB0_219
	v_and_b32_e32 v0, 64, v224
	v_add_u32_e32 v1, 64, v0
	v_xor_b32_e32 v2, 32, v224
	v_cmp_lt_i32_e32 vcc, v2, v1
	v_xor_b32_e32 v3, 16, v224
	v_xor_b32_e32 v4, 8, v224
	v_cndmask_b32_e32 v2, v224, v2, vcc
	v_cmp_lt_i32_e32 vcc, v3, v1
	v_xor_b32_e32 v5, 4, v224
	v_xor_b32_e32 v6, 2, v224
	v_cndmask_b32_e32 v3, v224, v3, vcc
	v_cmp_lt_i32_e32 vcc, v4, v1
	v_xor_b32_e32 v7, 1, v224
	v_readlane_b32 s2, v245, 61
	v_cndmask_b32_e32 v4, v224, v4, vcc
	v_cmp_lt_i32_e32 vcc, v5, v1
	v_lshlrev_b32_e32 v2, 2, v2
	v_lshlrev_b32_e32 v3, 2, v3
	v_cndmask_b32_e32 v5, v224, v5, vcc
	v_cmp_lt_i32_e32 vcc, v6, v1
	v_lshlrev_b32_e32 v4, 2, v4
	v_lshlrev_b32_e32 v5, 2, v5
	v_cndmask_b32_e32 v6, v224, v6, vcc
	v_cmp_lt_i32_e32 vcc, v7, v1
	v_lshlrev_b32_e32 v6, 2, v6
	s_lshl_b32 s8, s2, 3
	v_cndmask_b32_e32 v1, v224, v7, vcc
	v_lshlrev_b32_e32 v7, 2, v1
	v_add_u32_e32 v1, -1, v224
	v_cmp_lt_i32_e32 vcc, v1, v0
	s_mov_b64 s[2:3], 0
	v_mov_b32_e32 v14, v214
	v_cndmask_b32_e32 v1, v1, v224, vcc
	v_lshlrev_b32_e32 v8, 2, v1
	v_add_u32_e32 v1, -2, v224
	v_cmp_lt_i32_e32 vcc, v1, v0
	s_nop 1
	v_cndmask_b32_e32 v1, v1, v224, vcc
	v_lshlrev_b32_e32 v9, 2, v1
	v_add_u32_e32 v1, -4, v224
	v_cmp_lt_i32_e32 vcc, v1, v0
	s_nop 1
	v_cndmask_b32_e32 v1, v1, v224, vcc
	v_lshlrev_b32_e32 v10, 2, v1
	v_add_u32_e32 v1, -8, v224
	v_cmp_lt_i32_e32 vcc, v1, v0
	s_nop 1
	v_cndmask_b32_e32 v1, v1, v224, vcc
	v_lshlrev_b32_e32 v11, 2, v1
	v_add_u32_e32 v1, -16, v224
	v_cmp_lt_i32_e32 vcc, v1, v0
	s_nop 1
	v_cndmask_b32_e32 v1, v1, v224, vcc
	v_lshlrev_b32_e32 v12, 2, v1
	v_subrev_u32_e32 v1, 32, v224
	v_cmp_lt_i32_e32 vcc, v1, v0
	s_nop 1
	v_cndmask_b32_e32 v0, v1, v224, vcc
	v_lshlrev_b32_e32 v13, 2, v0
	v_readfirstlane_b32 s6, v214
	s_nop 1
	s_cmp_lt_u32 s6, 0x440
	s_cbranch_scc1 .LBB0_219
	v_add_u32_e32 v14, 0xfffffbc0, v214
	v_readlane_b32 s68, v245, 34
	v_readlane_b32 s69, v245, 35
	v_readlane_b32 s70, v245, 10
	v_readlane_b32 s71, v245, 11
	v_readlane_b32 s72, v245, 63
	v_readlane_b32 s73, v244, 0
	v_readlane_b32 s74, v244, 1
	v_readlane_b32 s75, v244, 2
	v_readlane_b32 s76, v244, 3
	v_readlane_b32 s77, v244, 4
	v_readlane_b32 s78, v244, 5
	v_readlane_b32 s79, v244, 6
	v_readlane_b32 s80, v244, 7
	v_readlane_b32 s81, v244, 8
	v_readlane_b32 s82, v244, 9
	v_readlane_b32 s83, v244, 10
	s_movk_i32 s9, 0x2080
.Lfc_loop:
	v_mul_u32_u24_sdwa v23, v14, s16 dst_sel:DWORD dst_unused:UNUSED_PAD src0_sel:WORD_0 src1_sel:DWORD
	v_lshrrev_b32_e32 v15, 19, v23
	v_mul_lo_u16_e32 v23, 0x82, v15
	v_sub_u16_e32 v16, v14, v23
	v_mul_u32_u24_e32 v23, 0x82, v15
	v_add_lshl_u32 v178, v23, v176, 2
	v_lshrrev_b32_e32 v23, 3, v15
	v_and_b32_e32 v24, 7, v15
	v_lshl_add_u64 v[26:27], s[68:69], 0, v[178:179]
	v_lshl_or_b32 v0, v16, 6, v176
	global_load_dword v20, v[26:27], off
	global_load_dword v21, v[26:27], off offset:256
	global_load_dword v22, v[26:27], off offset:512
	v_mad_u32_u24 v23, v23, s9, v0
	v_mul_u32_u24_e32 v23, 0x1618, v23
	v_or_b32_e32 v178, v23, v24
	v_lshl_add_u64 v[26:27], v[178:179], 1, s[56:57]
	v_or_b32_e32 v178, s8, v24
	global_load_ushort v25, v[26:27], off offset:3072
	v_lshl_add_u64 v[26:27], v[178:179], 2, s[70:71]
	global_load_dword v26, v[26:27], off
	v_add_u32_e32 v28, 0x3c0, v14
	s_nop 0
	v_readfirstlane_b32 s6, v28
	s_cmp_le_u32 s6, s37
	s_cselect_b32 s7, 1, 0
	s_min_u32 s6, s6, s37
	v_mov_b32_e32 v28, s6
	s_nop 1
	v_mul_u32_u24_sdwa v37, v28, s16 dst_sel:DWORD dst_unused:UNUSED_PAD src0_sel:WORD_0 src1_sel:DWORD
	v_lshrrev_b32_e32 v29, 19, v37
	v_mul_lo_u16_e32 v37, 0x82, v29
	v_sub_u16_e32 v30, v28, v37
	v_mul_u32_u24_e32 v37, 0x82, v29
	v_add_lshl_u32 v178, v37, v176, 2
	v_lshrrev_b32_e32 v37, 3, v29
	v_and_b32_e32 v38, 7, v29
	v_lshl_add_u64 v[40:41], s[68:69], 0, v[178:179]
	v_lshl_or_b32 v31, v30, 6, v176
	global_load_dword v32, v[40:41], off
	global_load_dword v33, v[40:41], off offset:256
	global_load_dword v34, v[40:41], off offset:512
	v_mad_u32_u24 v37, v37, s9, v31
	v_mul_u32_u24_e32 v37, 0x1618, v37
	v_or_b32_e32 v178, v37, v38
	v_lshl_add_u64 v[40:41], v[178:179], 1, s[56:57]
	v_or_b32_e32 v178, s8, v38
	global_load_ushort v35, v[40:41], off offset:3072
	v_lshl_add_u64 v[40:41], v[178:179], 2, s[70:71]
	global_load_dword v36, v[40:41], off
	s_waitcnt vmcnt(7)
	v_cmp_lt_u32_e32 vcc, v176, v16
	s_nop 1
	v_cndmask_b32_e32 v17, 0, v20, vcc
	v_add_f32_e32 v17, 0, v17
	v_cmp_lt_u32_e32 vcc, v215, v16
	s_nop 1
	v_cndmask_b32_e32 v18, 0, v21, vcc
	v_add_f32_e32 v17, v17, v18
	v_cmp_lt_u32_e32 vcc, v216, v16
	s_nop 1
	v_cndmask_b32_e32 v18, 0, v22, vcc
	v_add_f32_e32 v17, v17, v18
	ds_bpermute_b32 v18, v2, v17
	s_waitcnt lgkmcnt(0)
	v_add_f32_e32 v18, v17, v18
	ds_bpermute_b32 v19, v3, v18
	s_waitcnt lgkmcnt(0)
	v_add_f32_e32 v18, v18, v19
	ds_bpermute_b32 v19, v4, v18
	s_waitcnt lgkmcnt(0)
	v_add_f32_e32 v18, v18, v19
	ds_bpermute_b32 v19, v5, v18
	s_waitcnt lgkmcnt(0)
	v_add_f32_e32 v18, v18, v19
	ds_bpermute_b32 v19, v6, v18
	s_waitcnt lgkmcnt(0)
	v_add_f32_e32 v1, v18, v19
	ds_bpermute_b32 v17, v7, v1
	s_waitcnt vmcnt(5)
	v_lshlrev_b32_e32 v25, 16, v25
	v_add_f32_e32 v25, v26, v25
	v_mul_f32_e64 v26, |v25|, s98
	v_exp_f32_e32 v26, v26
	v_min_f32_e32 v25, 0, v25
	v_add_f32_e32 v26, 1.0, v26
	v_log_f32_e32 v26, v26
	s_nop 0
	v_fmac_f32_e32 v25, 0xbf317218, v26
	v_cmp_lt_u32_e32 vcc, s46, v0
	s_nop 1
	v_cndmask_b32_e32 v16, 0, v25, vcc
	s_waitcnt lgkmcnt(0)
	v_add_f32_e32 v1, v1, v17
	ds_bpermute_b32 v17, v8, v16
	v_mul_u32_u24_e32 v15, 0x2080, v15
	s_waitcnt lgkmcnt(0)
	v_add_f32_e32 v17, v16, v17
	v_cndmask_b32_e64 v16, v17, v16, s[72:73]
	ds_bpermute_b32 v17, v9, v16
	v_add_lshl_u32 v0, v0, v15, 2
	s_waitcnt lgkmcnt(0)
	v_add_f32_e32 v17, v16, v17
	v_cndmask_b32_e64 v16, v17, v16, s[74:75]
	ds_bpermute_b32 v17, v10, v16
	s_waitcnt lgkmcnt(0)
	v_add_f32_e32 v17, v16, v17
	v_cndmask_b32_e64 v16, v17, v16, s[76:77]
	ds_bpermute_b32 v17, v11, v16
	s_waitcnt lgkmcnt(0)
	v_add_f32_e32 v17, v16, v17
	v_cndmask_b32_e64 v16, v17, v16, s[78:79]
	ds_bpermute_b32 v17, v12, v16
	s_waitcnt lgkmcnt(0)
	v_add_f32_e32 v17, v16, v17
	v_cndmask_b32_e64 v16, v17, v16, s[80:81]
	ds_bpermute_b32 v17, v13, v16
	s_waitcnt lgkmcnt(0)
	v_add_f32_e32 v17, v16, v17
	v_cndmask_b32_e64 v16, v17, v16, s[82:83]
	v_add_f32_e32 v1, v1, v16
	global_store_dword v0, v1, s[60:61]
	s_cmp_eq_u32 s7, 0
	s_cbranch_scc1 .Lfc_noB
	s_waitcnt vmcnt(3)
	v_cmp_lt_u32_e32 vcc, v176, v30
	s_nop 1
	v_cndmask_b32_e32 v17, 0, v32, vcc
	v_add_f32_e32 v17, 0, v17
	v_cmp_lt_u32_e32 vcc, v215, v30
	s_nop 1
	v_cndmask_b32_e32 v18, 0, v33, vcc
	v_add_f32_e32 v17, v17, v18
	v_cmp_lt_u32_e32 vcc, v216, v30
	s_nop 1
	v_cndmask_b32_e32 v18, 0, v34, vcc
	v_add_f32_e32 v17, v17, v18
	ds_bpermute_b32 v18, v2, v17
	s_waitcnt lgkmcnt(0)
	v_add_f32_e32 v18, v17, v18
	ds_bpermute_b32 v19, v3, v18
	s_waitcnt lgkmcnt(0)
	v_add_f32_e32 v18, v18, v19
	ds_bpermute_b32 v19, v4, v18
	s_waitcnt lgkmcnt(0)
	v_add_f32_e32 v18, v18, v19
	ds_bpermute_b32 v19, v5, v18
	s_waitcnt lgkmcnt(0)
	v_add_f32_e32 v18, v18, v19
	ds_bpermute_b32 v19, v6, v18
	s_waitcnt lgkmcnt(0)
	v_add_f32_e32 v1, v18, v19
	ds_bpermute_b32 v17, v7, v1
	s_waitcnt vmcnt(1)
	v_lshlrev_b32_e32 v35, 16, v35
	v_add_f32_e32 v35, v36, v35
	v_mul_f32_e64 v36, |v35|, s98
	v_exp_f32_e32 v36, v36
	v_min_f32_e32 v35, 0, v35
	v_add_f32_e32 v36, 1.0, v36
	v_log_f32_e32 v36, v36
	s_nop 0
	v_fmac_f32_e32 v35, 0xbf317218, v36
	v_cmp_lt_u32_e32 vcc, s46, v31
	s_nop 1
	v_cndmask_b32_e32 v30, 0, v35, vcc
	s_waitcnt lgkmcnt(0)
	v_add_f32_e32 v1, v1, v17
	ds_bpermute_b32 v17, v8, v30
	v_mul_u32_u24_e32 v29, 0x2080, v29
	s_waitcnt lgkmcnt(0)
	v_add_f32_e32 v17, v30, v17
	v_cndmask_b32_e64 v30, v17, v30, s[72:73]
	ds_bpermute_b32 v17, v9, v30
	v_add_lshl_u32 v31, v31, v29, 2
	s_waitcnt lgkmcnt(0)
	v_add_f32_e32 v17, v30, v17
	v_cndmask_b32_e64 v30, v17, v30, s[74:75]
	ds_bpermute_b32 v17, v10, v30
	s_waitcnt lgkmcnt(0)
	v_add_f32_e32 v17, v30, v17
	v_cndmask_b32_e64 v30, v17, v30, s[76:77]
	ds_bpermute_b32 v17, v11, v30
	s_waitcnt lgkmcnt(0)
	v_add_f32_e32 v17, v30, v17
	v_cndmask_b32_e64 v30, v17, v30, s[78:79]
	ds_bpermute_b32 v17, v12, v30
	s_waitcnt lgkmcnt(0)
	v_add_f32_e32 v17, v30, v17
	v_cndmask_b32_e64 v30, v17, v30, s[80:81]
	ds_bpermute_b32 v17, v13, v30
	s_waitcnt lgkmcnt(0)
	v_add_f32_e32 v17, v30, v17
	v_cndmask_b32_e64 v30, v17, v30, s[82:83]
	v_add_f32_e32 v1, v1, v30
	global_store_dword v31, v1, s[60:61]
.Lfc_noB:
	s_waitcnt vmcnt(0)
	v_add_u32_e32 v14, 0x780, v14
	s_nop 0
	v_readfirstlane_b32 s6, v14
	s_cmp_le_u32 s6, s37
	s_cbranch_scc1 .Lfc_loop
